# moe2 epilogue: quad 4x4 transposes via DPP, 8-byte stores (32 per lane instead of 128 two-byte stores)
# baseline (speedup 1.0000x reference)
; DI u16 f2bf(float a) { return (u16)(pack2(a, 0.f) & 0xffffu); }
; DI void moe2_phase(const P& p, int l, unsigned char* lds) {
;     ...
;     const float* b2 = p.in[I_BE2] + (size_t)(l * 32 + e) * 1024;
;     u16* ybase = Y + (size_t)(m0 + wm * 128 + 4 * hh) * 1024 + n0 + wn * 64 + r;
; #pragma unroll
;     for (int nt = 0; nt < 2; ++nt) {
;       float bv = b2[n0 + wn * 64 + nt * 32 + r];
; #pragma unroll
;       for (int mt = 0; mt < 4; ++mt)
; #pragma unroll
;         for (int i = 0; i < 16; ++i)
;           ybase[(size_t)(mt * 32 + 8 * (i >> 2) + (i & 3)) * 1024 + nt * 32] = f2bf(acc[mt][nt][i] + bv);
;     }
.LBB0_1476:
	s_or_b64 exec, exec, s[0:1]
	s_waitcnt vmcnt(6)
	v_add_u32_e32 v130, s52, v172
	s_lshl_b32 s0, s8, 8
	v_ashrrev_i32_e32 v131, 31, v130
	v_readlane_b32 s24, v252, 0
	v_lshlrev_b64 v[130:131], 12, v[130:131]
	v_readlane_b32 s28, v252, 4
	v_readlane_b32 s29, v252, 5
	v_or_b32_e32 v134, s0, v181
	v_ashrrev_i32_e32 v135, 31, v134
	v_lshl_add_u64 v[132:133], s[28:29], 0, v[130:131]
	v_lshl_add_u64 v[134:135], v[134:135], 2, v[132:133]
	global_load_dword v136, v[134:135], off
	v_lshl_add_u32 v130, s6, 8, v180
	v_ashrrev_i32_e32 v131, 31, v130
	v_readlane_b32 s6, v253, 20
	v_lshlrev_b64 v[130:131], 11, v[130:131]
	v_readlane_b32 s7, v253, 21
	s_ashr_i32 s1, s0, 31
	v_mov_b32_e32 v171, v179
	v_lshl_add_u64 v[130:131], s[6:7], 0, v[130:131]
	v_lshl_add_u64 v[130:131], s[0:1], 1, v[130:131]
	v_lshl_add_u64 v[130:131], v[130:131], 0, v[178:179]
	v_lshl_add_u64 v[130:131], v[130:131], 0, v[170:171]
	v_readlane_b32 s25, v252, 1
	v_readlane_b32 s26, v252, 2
	v_readlane_b32 s27, v252, 3
	v_readlane_b32 s30, v252, 6
	v_readlane_b32 s31, v252, 7
	global_load_dword v137, v[134:135], off offset:128
	v_and_b32_e32 v138, 3, v215
	v_and_b32_e32 v150, 1, v215
	v_mul_u32_u24_e32 v154, 0x7fe, v138
	v_mov_b32_e32 v155, 0
	v_mov_b32_e32 v139, 0x5040100
	v_mov_b32_e32 v152, 0x3020706
	v_cmp_eq_u32_e32 vcc, 1, v150
	s_mov_b64 s[0:1], 0x4000
	v_lshl_add_u64 v[130:131], v[130:131], 0, v[154:155]
	s_nop 0
	v_cndmask_b32_e32 v139, v139, v152, vcc
	v_cmp_lt_u32_e32 vcc, 1, v138
	s_waitcnt vmcnt(0)
	v_add_f32_e32 v114, v114, v136
	v_add_f32_e32 v115, v115, v136
	v_add_f32_e32 v116, v116, v136
	v_add_f32_e32 v117, v117, v136
	v_cvt_pk_bf16_f32 v140, v114, v115
	v_cvt_pk_bf16_f32 v141, v116, v117
	s_nop 0
	v_mov_b32_dpp v142, v140 quad_perm:[1,0,3,2] row_mask:0xf bank_mask:0xf
	v_mov_b32_dpp v143, v141 quad_perm:[1,0,3,2] row_mask:0xf bank_mask:0xf
	v_perm_b32 v144, v142, v140, v139
	v_perm_b32 v145, v143, v141, v139
	s_nop 0
	v_mov_b32_dpp v146, v144 quad_perm:[2,3,0,1] row_mask:0xf bank_mask:0xf
	v_mov_b32_dpp v147, v145 quad_perm:[2,3,0,1] row_mask:0xf bank_mask:0xf
	v_cndmask_b32_e32 v148, v144, v147, vcc
	v_cndmask_b32_e32 v149, v146, v145, vcc
	global_store_dwordx2 v[130:131], v[148:149], off
	v_add_f32_e32 v50, v50, v137
	v_add_f32_e32 v51, v51, v137
	v_add_f32_e32 v52, v52, v137
	v_add_f32_e32 v53, v53, v137
	v_cvt_pk_bf16_f32 v140, v50, v51
	v_cvt_pk_bf16_f32 v141, v52, v53
	s_nop 0
	v_mov_b32_dpp v142, v140 quad_perm:[1,0,3,2] row_mask:0xf bank_mask:0xf
	v_mov_b32_dpp v143, v141 quad_perm:[1,0,3,2] row_mask:0xf bank_mask:0xf
	v_perm_b32 v144, v142, v140, v139
	v_perm_b32 v145, v143, v141, v139
	s_nop 0
	v_mov_b32_dpp v146, v144 quad_perm:[2,3,0,1] row_mask:0xf bank_mask:0xf
	v_mov_b32_dpp v147, v145 quad_perm:[2,3,0,1] row_mask:0xf bank_mask:0xf
	v_cndmask_b32_e32 v148, v144, v147, vcc
	v_cndmask_b32_e32 v149, v146, v145, vcc
	global_store_dwordx2 v[130:131], v[148:149], off offset:64
	v_lshl_add_u64 v[130:131], v[130:131], 0, s[0:1]
	v_add_f32_e32 v118, v118, v136
	v_add_f32_e32 v119, v119, v136
	v_add_f32_e32 v120, v120, v136
	v_add_f32_e32 v121, v121, v136
	v_cvt_pk_bf16_f32 v140, v118, v119
	v_cvt_pk_bf16_f32 v141, v120, v121
	s_nop 0
	v_mov_b32_dpp v142, v140 quad_perm:[1,0,3,2] row_mask:0xf bank_mask:0xf
	v_mov_b32_dpp v143, v141 quad_perm:[1,0,3,2] row_mask:0xf bank_mask:0xf
	v_perm_b32 v144, v142, v140, v139
	v_perm_b32 v145, v143, v141, v139
	s_nop 0
	v_mov_b32_dpp v146, v144 quad_perm:[2,3,0,1] row_mask:0xf bank_mask:0xf
	v_mov_b32_dpp v147, v145 quad_perm:[2,3,0,1] row_mask:0xf bank_mask:0xf
	v_cndmask_b32_e32 v148, v144, v147, vcc
	v_cndmask_b32_e32 v149, v146, v145, vcc
	global_store_dwordx2 v[130:131], v[148:149], off
	v_add_f32_e32 v54, v54, v137
	v_add_f32_e32 v55, v55, v137
	v_add_f32_e32 v56, v56, v137
	v_add_f32_e32 v57, v57, v137
	v_cvt_pk_bf16_f32 v140, v54, v55
	v_cvt_pk_bf16_f32 v141, v56, v57
	s_nop 0
	v_mov_b32_dpp v142, v140 quad_perm:[1,0,3,2] row_mask:0xf bank_mask:0xf
	v_mov_b32_dpp v143, v141 quad_perm:[1,0,3,2] row_mask:0xf bank_mask:0xf
	v_perm_b32 v144, v142, v140, v139
	v_perm_b32 v145, v143, v141, v139
	s_nop 0
	v_mov_b32_dpp v146, v144 quad_perm:[2,3,0,1] row_mask:0xf bank_mask:0xf
	v_mov_b32_dpp v147, v145 quad_perm:[2,3,0,1] row_mask:0xf bank_mask:0xf
	v_cndmask_b32_e32 v148, v144, v147, vcc
	v_cndmask_b32_e32 v149, v146, v145, vcc
	global_store_dwordx2 v[130:131], v[148:149], off offset:64
	v_lshl_add_u64 v[130:131], v[130:131], 0, s[0:1]
	v_add_f32_e32 v122, v122, v136
	v_add_f32_e32 v123, v123, v136
	v_add_f32_e32 v124, v124, v136
	v_add_f32_e32 v125, v125, v136
	v_cvt_pk_bf16_f32 v140, v122, v123
	v_cvt_pk_bf16_f32 v141, v124, v125
	s_nop 0
	v_mov_b32_dpp v142, v140 quad_perm:[1,0,3,2] row_mask:0xf bank_mask:0xf
	v_mov_b32_dpp v143, v141 quad_perm:[1,0,3,2] row_mask:0xf bank_mask:0xf
	v_perm_b32 v144, v142, v140, v139
	v_perm_b32 v145, v143, v141, v139
	s_nop 0
	v_mov_b32_dpp v146, v144 quad_perm:[2,3,0,1] row_mask:0xf bank_mask:0xf
	v_mov_b32_dpp v147, v145 quad_perm:[2,3,0,1] row_mask:0xf bank_mask:0xf
	v_cndmask_b32_e32 v148, v144, v147, vcc
	v_cndmask_b32_e32 v149, v146, v145, vcc
	global_store_dwordx2 v[130:131], v[148:149], off
	v_add_f32_e32 v58, v58, v137
	v_add_f32_e32 v59, v59, v137
	v_add_f32_e32 v60, v60, v137
	v_add_f32_e32 v61, v61, v137
	v_cvt_pk_bf16_f32 v140, v58, v59
	v_cvt_pk_bf16_f32 v141, v60, v61
	s_nop 0
	v_mov_b32_dpp v142, v140 quad_perm:[1,0,3,2] row_mask:0xf bank_mask:0xf
	v_mov_b32_dpp v143, v141 quad_perm:[1,0,3,2] row_mask:0xf bank_mask:0xf
	v_perm_b32 v144, v142, v140, v139
	v_perm_b32 v145, v143, v141, v139
	s_nop 0
	v_mov_b32_dpp v146, v144 quad_perm:[2,3,0,1] row_mask:0xf bank_mask:0xf
; DI u16 f2bf(float a) { return (u16)(pack2(a, 0.f) & 0xffffu); }
; DI void moe2_phase(const P& p, int l, unsigned char* lds) {
;     ...
;     const float* b2 = p.in[I_BE2] + (size_t)(l * 32 + e) * 1024;
;     u16* ybase = Y + (size_t)(m0 + wm * 128 + 4 * hh) * 1024 + n0 + wn * 64 + r;
; #pragma unroll
;     for (int nt = 0; nt < 2; ++nt) {
;       float bv = b2[n0 + wn * 64 + nt * 32 + r];
; #pragma unroll
;       for (int mt = 0; mt < 4; ++mt)
; #pragma unroll
;         for (int i = 0; i < 16; ++i)
;           ybase[(size_t)(mt * 32 + 8 * (i >> 2) + (i & 3)) * 1024 + nt * 32] = f2bf(acc[mt][nt][i] + bv);
;     }
	v_mov_b32_dpp v147, v145 quad_perm:[2,3,0,1] row_mask:0xf bank_mask:0xf
	v_cndmask_b32_e32 v148, v144, v147, vcc
	v_cndmask_b32_e32 v149, v146, v145, vcc
	global_store_dwordx2 v[130:131], v[148:149], off offset:64
	v_lshl_add_u64 v[130:131], v[130:131], 0, s[0:1]
	v_add_f32_e32 v126, v126, v136
	v_add_f32_e32 v127, v127, v136
	v_add_f32_e32 v128, v128, v136
	v_add_f32_e32 v129, v129, v136
	v_cvt_pk_bf16_f32 v140, v126, v127
	v_cvt_pk_bf16_f32 v141, v128, v129
	s_nop 0
	v_mov_b32_dpp v142, v140 quad_perm:[1,0,3,2] row_mask:0xf bank_mask:0xf
	v_mov_b32_dpp v143, v141 quad_perm:[1,0,3,2] row_mask:0xf bank_mask:0xf
	v_perm_b32 v144, v142, v140, v139
	v_perm_b32 v145, v143, v141, v139
	s_nop 0
	v_mov_b32_dpp v146, v144 quad_perm:[2,3,0,1] row_mask:0xf bank_mask:0xf
	v_mov_b32_dpp v147, v145 quad_perm:[2,3,0,1] row_mask:0xf bank_mask:0xf
	v_cndmask_b32_e32 v148, v144, v147, vcc
	v_cndmask_b32_e32 v149, v146, v145, vcc
	global_store_dwordx2 v[130:131], v[148:149], off
	v_add_f32_e32 v62, v62, v137
	v_add_f32_e32 v63, v63, v137
	v_add_f32_e32 v64, v64, v137
	v_add_f32_e32 v65, v65, v137
	v_cvt_pk_bf16_f32 v140, v62, v63
	v_cvt_pk_bf16_f32 v141, v64, v65
	s_nop 0
	v_mov_b32_dpp v142, v140 quad_perm:[1,0,3,2] row_mask:0xf bank_mask:0xf
	v_mov_b32_dpp v143, v141 quad_perm:[1,0,3,2] row_mask:0xf bank_mask:0xf
	v_perm_b32 v144, v142, v140, v139
	v_perm_b32 v145, v143, v141, v139
	s_nop 0
	v_mov_b32_dpp v146, v144 quad_perm:[2,3,0,1] row_mask:0xf bank_mask:0xf
	v_mov_b32_dpp v147, v145 quad_perm:[2,3,0,1] row_mask:0xf bank_mask:0xf
	v_cndmask_b32_e32 v148, v144, v147, vcc
	v_cndmask_b32_e32 v149, v146, v145, vcc
	global_store_dwordx2 v[130:131], v[148:149], off offset:64
	v_lshl_add_u64 v[130:131], v[130:131], 0, s[0:1]
	v_add_f32_e32 v98, v98, v136
	v_add_f32_e32 v99, v99, v136
	v_add_f32_e32 v100, v100, v136
	v_add_f32_e32 v101, v101, v136
	v_cvt_pk_bf16_f32 v140, v98, v99
	v_cvt_pk_bf16_f32 v141, v100, v101
	s_nop 0
	v_mov_b32_dpp v142, v140 quad_perm:[1,0,3,2] row_mask:0xf bank_mask:0xf
	v_mov_b32_dpp v143, v141 quad_perm:[1,0,3,2] row_mask:0xf bank_mask:0xf
	v_perm_b32 v144, v142, v140, v139
	v_perm_b32 v145, v143, v141, v139
	s_nop 0
	v_mov_b32_dpp v146, v144 quad_perm:[2,3,0,1] row_mask:0xf bank_mask:0xf
	v_mov_b32_dpp v147, v145 quad_perm:[2,3,0,1] row_mask:0xf bank_mask:0xf
	v_cndmask_b32_e32 v148, v144, v147, vcc
	v_cndmask_b32_e32 v149, v146, v145, vcc
	global_store_dwordx2 v[130:131], v[148:149], off
	v_add_f32_e32 v34, v34, v137
	v_add_f32_e32 v35, v35, v137
	v_add_f32_e32 v36, v36, v137
	v_add_f32_e32 v37, v37, v137
	v_cvt_pk_bf16_f32 v140, v34, v35
	v_cvt_pk_bf16_f32 v141, v36, v37
	s_nop 0
	v_mov_b32_dpp v142, v140 quad_perm:[1,0,3,2] row_mask:0xf bank_mask:0xf
	v_mov_b32_dpp v143, v141 quad_perm:[1,0,3,2] row_mask:0xf bank_mask:0xf
	v_perm_b32 v144, v142, v140, v139
	v_perm_b32 v145, v143, v141, v139
	s_nop 0
	v_mov_b32_dpp v146, v144 quad_perm:[2,3,0,1] row_mask:0xf bank_mask:0xf
	v_mov_b32_dpp v147, v145 quad_perm:[2,3,0,1] row_mask:0xf bank_mask:0xf
	v_cndmask_b32_e32 v148, v144, v147, vcc
	v_cndmask_b32_e32 v149, v146, v145, vcc
	global_store_dwordx2 v[130:131], v[148:149], off offset:64
	v_lshl_add_u64 v[130:131], v[130:131], 0, s[0:1]
	v_add_f32_e32 v102, v102, v136
	v_add_f32_e32 v103, v103, v136
	v_add_f32_e32 v104, v104, v136
	v_add_f32_e32 v105, v105, v136
	v_cvt_pk_bf16_f32 v140, v102, v103
	v_cvt_pk_bf16_f32 v141, v104, v105
	s_nop 0
	v_mov_b32_dpp v142, v140 quad_perm:[1,0,3,2] row_mask:0xf bank_mask:0xf
	v_mov_b32_dpp v143, v141 quad_perm:[1,0,3,2] row_mask:0xf bank_mask:0xf
	v_perm_b32 v144, v142, v140, v139
	v_perm_b32 v145, v143, v141, v139
	s_nop 0
	v_mov_b32_dpp v146, v144 quad_perm:[2,3,0,1] row_mask:0xf bank_mask:0xf
	v_mov_b32_dpp v147, v145 quad_perm:[2,3,0,1] row_mask:0xf bank_mask:0xf
	v_cndmask_b32_e32 v148, v144, v147, vcc
	v_cndmask_b32_e32 v149, v146, v145, vcc
	global_store_dwordx2 v[130:131], v[148:149], off
	v_add_f32_e32 v38, v38, v137
	v_add_f32_e32 v39, v39, v137
	v_add_f32_e32 v40, v40, v137
	v_add_f32_e32 v41, v41, v137
	v_cvt_pk_bf16_f32 v140, v38, v39
	v_cvt_pk_bf16_f32 v141, v40, v41
	s_nop 0
	v_mov_b32_dpp v142, v140 quad_perm:[1,0,3,2] row_mask:0xf bank_mask:0xf
	v_mov_b32_dpp v143, v141 quad_perm:[1,0,3,2] row_mask:0xf bank_mask:0xf
	v_perm_b32 v144, v142, v140, v139
	v_perm_b32 v145, v143, v141, v139
	s_nop 0
	v_mov_b32_dpp v146, v144 quad_perm:[2,3,0,1] row_mask:0xf bank_mask:0xf
	v_mov_b32_dpp v147, v145 quad_perm:[2,3,0,1] row_mask:0xf bank_mask:0xf
	v_cndmask_b32_e32 v148, v144, v147, vcc
	v_cndmask_b32_e32 v149, v146, v145, vcc
	global_store_dwordx2 v[130:131], v[148:149], off offset:64
	v_lshl_add_u64 v[130:131], v[130:131], 0, s[0:1]
	v_add_f32_e32 v106, v106, v136
	v_add_f32_e32 v107, v107, v136
	v_add_f32_e32 v108, v108, v136
	v_add_f32_e32 v109, v109, v136
	v_cvt_pk_bf16_f32 v140, v106, v107
	v_cvt_pk_bf16_f32 v141, v108, v109
	s_nop 0
	v_mov_b32_dpp v142, v140 quad_perm:[1,0,3,2] row_mask:0xf bank_mask:0xf
	v_mov_b32_dpp v143, v141 quad_perm:[1,0,3,2] row_mask:0xf bank_mask:0xf
	v_perm_b32 v144, v142, v140, v139
	v_perm_b32 v145, v143, v141, v139
	s_nop 0
	v_mov_b32_dpp v146, v144 quad_perm:[2,3,0,1] row_mask:0xf bank_mask:0xf
	v_mov_b32_dpp v147, v145 quad_perm:[2,3,0,1] row_mask:0xf bank_mask:0xf
	v_cndmask_b32_e32 v148, v144, v147, vcc
	v_cndmask_b32_e32 v149, v146, v145, vcc
	global_store_dwordx2 v[130:131], v[148:149], off
	v_add_f32_e32 v42, v42, v137
	v_add_f32_e32 v43, v43, v137
	v_add_f32_e32 v44, v44, v137
	v_add_f32_e32 v45, v45, v137
	v_cvt_pk_bf16_f32 v140, v42, v43
	v_cvt_pk_bf16_f32 v141, v44, v45
	s_nop 0
	v_mov_b32_dpp v142, v140 quad_perm:[1,0,3,2] row_mask:0xf bank_mask:0xf
; DI u16 f2bf(float a) { return (u16)(pack2(a, 0.f) & 0xffffu); }
; DI void moe2_phase(const P& p, int l, unsigned char* lds) {
;     ...
;     const float* b2 = p.in[I_BE2] + (size_t)(l * 32 + e) * 1024;
;     u16* ybase = Y + (size_t)(m0 + wm * 128 + 4 * hh) * 1024 + n0 + wn * 64 + r;
; #pragma unroll
;     for (int nt = 0; nt < 2; ++nt) {
;       float bv = b2[n0 + wn * 64 + nt * 32 + r];
; #pragma unroll
;       for (int mt = 0; mt < 4; ++mt)
; #pragma unroll
;         for (int i = 0; i < 16; ++i)
;           ybase[(size_t)(mt * 32 + 8 * (i >> 2) + (i & 3)) * 1024 + nt * 32] = f2bf(acc[mt][nt][i] + bv);
;     }
	v_mov_b32_dpp v143, v141 quad_perm:[1,0,3,2] row_mask:0xf bank_mask:0xf
	v_perm_b32 v144, v142, v140, v139
	v_perm_b32 v145, v143, v141, v139
	s_nop 0
	v_mov_b32_dpp v146, v144 quad_perm:[2,3,0,1] row_mask:0xf bank_mask:0xf
	v_mov_b32_dpp v147, v145 quad_perm:[2,3,0,1] row_mask:0xf bank_mask:0xf
	v_cndmask_b32_e32 v148, v144, v147, vcc
	v_cndmask_b32_e32 v149, v146, v145, vcc
	global_store_dwordx2 v[130:131], v[148:149], off offset:64
	v_lshl_add_u64 v[130:131], v[130:131], 0, s[0:1]
	v_add_f32_e32 v110, v110, v136
	v_add_f32_e32 v111, v111, v136
	v_add_f32_e32 v112, v112, v136
	v_add_f32_e32 v113, v113, v136
	v_cvt_pk_bf16_f32 v140, v110, v111
	v_cvt_pk_bf16_f32 v141, v112, v113
	s_nop 0
	v_mov_b32_dpp v142, v140 quad_perm:[1,0,3,2] row_mask:0xf bank_mask:0xf
	v_mov_b32_dpp v143, v141 quad_perm:[1,0,3,2] row_mask:0xf bank_mask:0xf
	v_perm_b32 v144, v142, v140, v139
	v_perm_b32 v145, v143, v141, v139
	s_nop 0
	v_mov_b32_dpp v146, v144 quad_perm:[2,3,0,1] row_mask:0xf bank_mask:0xf
	v_mov_b32_dpp v147, v145 quad_perm:[2,3,0,1] row_mask:0xf bank_mask:0xf
	v_cndmask_b32_e32 v148, v144, v147, vcc
	v_cndmask_b32_e32 v149, v146, v145, vcc
	global_store_dwordx2 v[130:131], v[148:149], off
	v_add_f32_e32 v46, v46, v137
	v_add_f32_e32 v47, v47, v137
	v_add_f32_e32 v48, v48, v137
	v_add_f32_e32 v49, v49, v137
	v_cvt_pk_bf16_f32 v140, v46, v47
	v_cvt_pk_bf16_f32 v141, v48, v49
	s_nop 0
	v_mov_b32_dpp v142, v140 quad_perm:[1,0,3,2] row_mask:0xf bank_mask:0xf
	v_mov_b32_dpp v143, v141 quad_perm:[1,0,3,2] row_mask:0xf bank_mask:0xf
	v_perm_b32 v144, v142, v140, v139
	v_perm_b32 v145, v143, v141, v139
	s_nop 0
	v_mov_b32_dpp v146, v144 quad_perm:[2,3,0,1] row_mask:0xf bank_mask:0xf
	v_mov_b32_dpp v147, v145 quad_perm:[2,3,0,1] row_mask:0xf bank_mask:0xf
	v_cndmask_b32_e32 v148, v144, v147, vcc
	v_cndmask_b32_e32 v149, v146, v145, vcc
	global_store_dwordx2 v[130:131], v[148:149], off offset:64
	v_lshl_add_u64 v[130:131], v[130:131], 0, s[0:1]
	v_add_f32_e32 v82, v82, v136
	v_add_f32_e32 v83, v83, v136
	v_add_f32_e32 v84, v84, v136
	v_add_f32_e32 v85, v85, v136
	v_cvt_pk_bf16_f32 v140, v82, v83
	v_cvt_pk_bf16_f32 v141, v84, v85
	s_nop 0
	v_mov_b32_dpp v142, v140 quad_perm:[1,0,3,2] row_mask:0xf bank_mask:0xf
	v_mov_b32_dpp v143, v141 quad_perm:[1,0,3,2] row_mask:0xf bank_mask:0xf
	v_perm_b32 v144, v142, v140, v139
	v_perm_b32 v145, v143, v141, v139
	s_nop 0
	v_mov_b32_dpp v146, v144 quad_perm:[2,3,0,1] row_mask:0xf bank_mask:0xf
	v_mov_b32_dpp v147, v145 quad_perm:[2,3,0,1] row_mask:0xf bank_mask:0xf
	v_cndmask_b32_e32 v148, v144, v147, vcc
	v_cndmask_b32_e32 v149, v146, v145, vcc
	global_store_dwordx2 v[130:131], v[148:149], off
	v_add_f32_e32 v18, v18, v137
	v_add_f32_e32 v19, v19, v137
	v_add_f32_e32 v20, v20, v137
	v_add_f32_e32 v21, v21, v137
	v_cvt_pk_bf16_f32 v140, v18, v19
	v_cvt_pk_bf16_f32 v141, v20, v21
	s_nop 0
	v_mov_b32_dpp v142, v140 quad_perm:[1,0,3,2] row_mask:0xf bank_mask:0xf
	v_mov_b32_dpp v143, v141 quad_perm:[1,0,3,2] row_mask:0xf bank_mask:0xf
	v_perm_b32 v144, v142, v140, v139
	v_perm_b32 v145, v143, v141, v139
	s_nop 0
	v_mov_b32_dpp v146, v144 quad_perm:[2,3,0,1] row_mask:0xf bank_mask:0xf
	v_mov_b32_dpp v147, v145 quad_perm:[2,3,0,1] row_mask:0xf bank_mask:0xf
	v_cndmask_b32_e32 v148, v144, v147, vcc
	v_cndmask_b32_e32 v149, v146, v145, vcc
	global_store_dwordx2 v[130:131], v[148:149], off offset:64
	v_lshl_add_u64 v[130:131], v[130:131], 0, s[0:1]
	v_add_f32_e32 v86, v86, v136
	v_add_f32_e32 v87, v87, v136
	v_add_f32_e32 v88, v88, v136
	v_add_f32_e32 v89, v89, v136
	v_cvt_pk_bf16_f32 v140, v86, v87
	v_cvt_pk_bf16_f32 v141, v88, v89
	s_nop 0
	v_mov_b32_dpp v142, v140 quad_perm:[1,0,3,2] row_mask:0xf bank_mask:0xf
	v_mov_b32_dpp v143, v141 quad_perm:[1,0,3,2] row_mask:0xf bank_mask:0xf
	v_perm_b32 v144, v142, v140, v139
	v_perm_b32 v145, v143, v141, v139
	s_nop 0
	v_mov_b32_dpp v146, v144 quad_perm:[2,3,0,1] row_mask:0xf bank_mask:0xf
	v_mov_b32_dpp v147, v145 quad_perm:[2,3,0,1] row_mask:0xf bank_mask:0xf
	v_cndmask_b32_e32 v148, v144, v147, vcc
	v_cndmask_b32_e32 v149, v146, v145, vcc
	global_store_dwordx2 v[130:131], v[148:149], off
	v_add_f32_e32 v22, v22, v137
	v_add_f32_e32 v23, v23, v137
	v_add_f32_e32 v24, v24, v137
	v_add_f32_e32 v25, v25, v137
	v_cvt_pk_bf16_f32 v140, v22, v23
	v_cvt_pk_bf16_f32 v141, v24, v25
	s_nop 0
	v_mov_b32_dpp v142, v140 quad_perm:[1,0,3,2] row_mask:0xf bank_mask:0xf
	v_mov_b32_dpp v143, v141 quad_perm:[1,0,3,2] row_mask:0xf bank_mask:0xf
	v_perm_b32 v144, v142, v140, v139
	v_perm_b32 v145, v143, v141, v139
	s_nop 0
	v_mov_b32_dpp v146, v144 quad_perm:[2,3,0,1] row_mask:0xf bank_mask:0xf
	v_mov_b32_dpp v147, v145 quad_perm:[2,3,0,1] row_mask:0xf bank_mask:0xf
	v_cndmask_b32_e32 v148, v144, v147, vcc
	v_cndmask_b32_e32 v149, v146, v145, vcc
	global_store_dwordx2 v[130:131], v[148:149], off offset:64
	v_lshl_add_u64 v[130:131], v[130:131], 0, s[0:1]
	v_add_f32_e32 v90, v90, v136
	v_add_f32_e32 v91, v91, v136
	v_add_f32_e32 v92, v92, v136
	v_add_f32_e32 v93, v93, v136
	v_cvt_pk_bf16_f32 v140, v90, v91
	v_cvt_pk_bf16_f32 v141, v92, v93
	s_nop 0
	v_mov_b32_dpp v142, v140 quad_perm:[1,0,3,2] row_mask:0xf bank_mask:0xf
	v_mov_b32_dpp v143, v141 quad_perm:[1,0,3,2] row_mask:0xf bank_mask:0xf
	v_perm_b32 v144, v142, v140, v139
	v_perm_b32 v145, v143, v141, v139
	s_nop 0
	v_mov_b32_dpp v146, v144 quad_perm:[2,3,0,1] row_mask:0xf bank_mask:0xf
	v_mov_b32_dpp v147, v145 quad_perm:[2,3,0,1] row_mask:0xf bank_mask:0xf
	v_cndmask_b32_e32 v148, v144, v147, vcc
	v_cndmask_b32_e32 v149, v146, v145, vcc
	global_store_dwordx2 v[130:131], v[148:149], off
	v_add_f32_e32 v26, v26, v137
	v_add_f32_e32 v27, v27, v137
; DI u16 f2bf(float a) { return (u16)(pack2(a, 0.f) & 0xffffu); }
; DI void moe2_phase(const P& p, int l, unsigned char* lds) {
;     ...
;     const float* b2 = p.in[I_BE2] + (size_t)(l * 32 + e) * 1024;
;     u16* ybase = Y + (size_t)(m0 + wm * 128 + 4 * hh) * 1024 + n0 + wn * 64 + r;
; #pragma unroll
;     for (int nt = 0; nt < 2; ++nt) {
;       float bv = b2[n0 + wn * 64 + nt * 32 + r];
; #pragma unroll
;       for (int mt = 0; mt < 4; ++mt)
; #pragma unroll
;         for (int i = 0; i < 16; ++i)
;           ybase[(size_t)(mt * 32 + 8 * (i >> 2) + (i & 3)) * 1024 + nt * 32] = f2bf(acc[mt][nt][i] + bv);
;     }
	v_add_f32_e32 v28, v28, v137
	v_add_f32_e32 v29, v29, v137
	v_cvt_pk_bf16_f32 v140, v26, v27
	v_cvt_pk_bf16_f32 v141, v28, v29
	s_nop 0
	v_mov_b32_dpp v142, v140 quad_perm:[1,0,3,2] row_mask:0xf bank_mask:0xf
	v_mov_b32_dpp v143, v141 quad_perm:[1,0,3,2] row_mask:0xf bank_mask:0xf
	v_perm_b32 v144, v142, v140, v139
	v_perm_b32 v145, v143, v141, v139
	s_nop 0
	v_mov_b32_dpp v146, v144 quad_perm:[2,3,0,1] row_mask:0xf bank_mask:0xf
	v_mov_b32_dpp v147, v145 quad_perm:[2,3,0,1] row_mask:0xf bank_mask:0xf
	v_cndmask_b32_e32 v148, v144, v147, vcc
	v_cndmask_b32_e32 v149, v146, v145, vcc
	global_store_dwordx2 v[130:131], v[148:149], off offset:64
	v_lshl_add_u64 v[130:131], v[130:131], 0, s[0:1]
	v_add_f32_e32 v94, v94, v136
	v_add_f32_e32 v95, v95, v136
	v_add_f32_e32 v96, v96, v136
	v_add_f32_e32 v97, v97, v136
	v_cvt_pk_bf16_f32 v140, v94, v95
	v_cvt_pk_bf16_f32 v141, v96, v97
	s_nop 0
	v_mov_b32_dpp v142, v140 quad_perm:[1,0,3,2] row_mask:0xf bank_mask:0xf
	v_mov_b32_dpp v143, v141 quad_perm:[1,0,3,2] row_mask:0xf bank_mask:0xf
	v_perm_b32 v144, v142, v140, v139
	v_perm_b32 v145, v143, v141, v139
	s_nop 0
	v_mov_b32_dpp v146, v144 quad_perm:[2,3,0,1] row_mask:0xf bank_mask:0xf
	v_mov_b32_dpp v147, v145 quad_perm:[2,3,0,1] row_mask:0xf bank_mask:0xf
	v_cndmask_b32_e32 v148, v144, v147, vcc
	v_cndmask_b32_e32 v149, v146, v145, vcc
	global_store_dwordx2 v[130:131], v[148:149], off
	v_add_f32_e32 v30, v30, v137
	v_add_f32_e32 v31, v31, v137
	v_add_f32_e32 v32, v32, v137
	v_add_f32_e32 v33, v33, v137
	v_cvt_pk_bf16_f32 v140, v30, v31
	v_cvt_pk_bf16_f32 v141, v32, v33
	s_nop 0
	v_mov_b32_dpp v142, v140 quad_perm:[1,0,3,2] row_mask:0xf bank_mask:0xf
	v_mov_b32_dpp v143, v141 quad_perm:[1,0,3,2] row_mask:0xf bank_mask:0xf
	v_perm_b32 v144, v142, v140, v139
	v_perm_b32 v145, v143, v141, v139
	s_nop 0
	v_mov_b32_dpp v146, v144 quad_perm:[2,3,0,1] row_mask:0xf bank_mask:0xf
	v_mov_b32_dpp v147, v145 quad_perm:[2,3,0,1] row_mask:0xf bank_mask:0xf
	v_cndmask_b32_e32 v148, v144, v147, vcc
	v_cndmask_b32_e32 v149, v146, v145, vcc
	global_store_dwordx2 v[130:131], v[148:149], off offset:64
	v_lshl_add_u64 v[130:131], v[130:131], 0, s[0:1]
	v_add_f32_e32 v66, v66, v136
	v_add_f32_e32 v67, v67, v136
	v_add_f32_e32 v68, v68, v136
	v_add_f32_e32 v69, v69, v136
	v_cvt_pk_bf16_f32 v140, v66, v67
	v_cvt_pk_bf16_f32 v141, v68, v69
	s_nop 0
	v_mov_b32_dpp v142, v140 quad_perm:[1,0,3,2] row_mask:0xf bank_mask:0xf
	v_mov_b32_dpp v143, v141 quad_perm:[1,0,3,2] row_mask:0xf bank_mask:0xf
	v_perm_b32 v144, v142, v140, v139
	v_perm_b32 v145, v143, v141, v139
	s_nop 0
	v_mov_b32_dpp v146, v144 quad_perm:[2,3,0,1] row_mask:0xf bank_mask:0xf
	v_mov_b32_dpp v147, v145 quad_perm:[2,3,0,1] row_mask:0xf bank_mask:0xf
	v_cndmask_b32_e32 v148, v144, v147, vcc
	v_cndmask_b32_e32 v149, v146, v145, vcc
	global_store_dwordx2 v[130:131], v[148:149], off
	v_add_f32_e32 v2, v2, v137
	v_add_f32_e32 v3, v3, v137
	v_add_f32_e32 v4, v4, v137
	v_add_f32_e32 v5, v5, v137
	v_cvt_pk_bf16_f32 v140, v2, v3
	v_cvt_pk_bf16_f32 v141, v4, v5
	s_nop 0
	v_mov_b32_dpp v142, v140 quad_perm:[1,0,3,2] row_mask:0xf bank_mask:0xf
	v_mov_b32_dpp v143, v141 quad_perm:[1,0,3,2] row_mask:0xf bank_mask:0xf
	v_perm_b32 v144, v142, v140, v139
	v_perm_b32 v145, v143, v141, v139
	s_nop 0
	v_mov_b32_dpp v146, v144 quad_perm:[2,3,0,1] row_mask:0xf bank_mask:0xf
	v_mov_b32_dpp v147, v145 quad_perm:[2,3,0,1] row_mask:0xf bank_mask:0xf
	v_cndmask_b32_e32 v148, v144, v147, vcc
	v_cndmask_b32_e32 v149, v146, v145, vcc
	global_store_dwordx2 v[130:131], v[148:149], off offset:64
	v_lshl_add_u64 v[130:131], v[130:131], 0, s[0:1]
	v_add_f32_e32 v70, v70, v136
	v_add_f32_e32 v71, v71, v136
	v_add_f32_e32 v72, v72, v136
	v_add_f32_e32 v73, v73, v136
	v_cvt_pk_bf16_f32 v140, v70, v71
	v_cvt_pk_bf16_f32 v141, v72, v73
	s_nop 0
	v_mov_b32_dpp v142, v140 quad_perm:[1,0,3,2] row_mask:0xf bank_mask:0xf
	v_mov_b32_dpp v143, v141 quad_perm:[1,0,3,2] row_mask:0xf bank_mask:0xf
; DI u16 f2bf(float a) { return (u16)(pack2(a, 0.f) & 0xffffu); }
; DI void moe2_phase(const P& p, int l, unsigned char* lds) {
;     ...
;     const float* b2 = p.in[I_BE2] + (size_t)(l * 32 + e) * 1024;
;     u16* ybase = Y + (size_t)(m0 + wm * 128 + 4 * hh) * 1024 + n0 + wn * 64 + r;
; #pragma unroll
;     for (int nt = 0; nt < 2; ++nt) {
;       float bv = b2[n0 + wn * 64 + nt * 32 + r];
; #pragma unroll
;       for (int mt = 0; mt < 4; ++mt)
; #pragma unroll
;         for (int i = 0; i < 16; ++i)
;           ybase[(size_t)(mt * 32 + 8 * (i >> 2) + (i & 3)) * 1024 + nt * 32] = f2bf(acc[mt][nt][i] + bv);
;     }
	v_perm_b32 v144, v142, v140, v139
	v_perm_b32 v145, v143, v141, v139
	s_nop 0
	v_mov_b32_dpp v146, v144 quad_perm:[2,3,0,1] row_mask:0xf bank_mask:0xf
	v_mov_b32_dpp v147, v145 quad_perm:[2,3,0,1] row_mask:0xf bank_mask:0xf
	v_cndmask_b32_e32 v148, v144, v147, vcc
	v_cndmask_b32_e32 v149, v146, v145, vcc
	global_store_dwordx2 v[130:131], v[148:149], off
	v_add_f32_e32 v6, v6, v137
	v_add_f32_e32 v7, v7, v137
	v_add_f32_e32 v8, v8, v137
	v_add_f32_e32 v9, v9, v137
	v_cvt_pk_bf16_f32 v140, v6, v7
	v_cvt_pk_bf16_f32 v141, v8, v9
	s_nop 0
	v_mov_b32_dpp v142, v140 quad_perm:[1,0,3,2] row_mask:0xf bank_mask:0xf
	v_mov_b32_dpp v143, v141 quad_perm:[1,0,3,2] row_mask:0xf bank_mask:0xf
	v_perm_b32 v144, v142, v140, v139
	v_perm_b32 v145, v143, v141, v139
	s_nop 0
	v_mov_b32_dpp v146, v144 quad_perm:[2,3,0,1] row_mask:0xf bank_mask:0xf
	v_mov_b32_dpp v147, v145 quad_perm:[2,3,0,1] row_mask:0xf bank_mask:0xf
	v_cndmask_b32_e32 v148, v144, v147, vcc
	v_cndmask_b32_e32 v149, v146, v145, vcc
	global_store_dwordx2 v[130:131], v[148:149], off offset:64
	v_lshl_add_u64 v[130:131], v[130:131], 0, s[0:1]
	v_add_f32_e32 v74, v74, v136
	v_add_f32_e32 v75, v75, v136
	v_add_f32_e32 v76, v76, v136
	v_add_f32_e32 v77, v77, v136
	v_cvt_pk_bf16_f32 v140, v74, v75
	v_cvt_pk_bf16_f32 v141, v76, v77
	s_nop 0
	v_mov_b32_dpp v142, v140 quad_perm:[1,0,3,2] row_mask:0xf bank_mask:0xf
	v_mov_b32_dpp v143, v141 quad_perm:[1,0,3,2] row_mask:0xf bank_mask:0xf
	v_perm_b32 v144, v142, v140, v139
	v_perm_b32 v145, v143, v141, v139
	s_nop 0
	v_mov_b32_dpp v146, v144 quad_perm:[2,3,0,1] row_mask:0xf bank_mask:0xf
	v_mov_b32_dpp v147, v145 quad_perm:[2,3,0,1] row_mask:0xf bank_mask:0xf
	v_cndmask_b32_e32 v148, v144, v147, vcc
	v_cndmask_b32_e32 v149, v146, v145, vcc
	global_store_dwordx2 v[130:131], v[148:149], off
	v_add_f32_e32 v10, v10, v137
	v_add_f32_e32 v11, v11, v137
	v_add_f32_e32 v12, v12, v137
	v_add_f32_e32 v13, v13, v137
	v_cvt_pk_bf16_f32 v140, v10, v11
	v_cvt_pk_bf16_f32 v141, v12, v13
	s_nop 0
	v_mov_b32_dpp v142, v140 quad_perm:[1,0,3,2] row_mask:0xf bank_mask:0xf
	v_mov_b32_dpp v143, v141 quad_perm:[1,0,3,2] row_mask:0xf bank_mask:0xf
	v_perm_b32 v144, v142, v140, v139
	v_perm_b32 v145, v143, v141, v139
	s_nop 0
	v_mov_b32_dpp v146, v144 quad_perm:[2,3,0,1] row_mask:0xf bank_mask:0xf
	v_mov_b32_dpp v147, v145 quad_perm:[2,3,0,1] row_mask:0xf bank_mask:0xf
	v_cndmask_b32_e32 v148, v144, v147, vcc
	v_cndmask_b32_e32 v149, v146, v145, vcc
	global_store_dwordx2 v[130:131], v[148:149], off offset:64
	v_lshl_add_u64 v[130:131], v[130:131], 0, s[0:1]
	v_add_f32_e32 v78, v78, v136
	v_add_f32_e32 v79, v79, v136
	v_add_f32_e32 v80, v80, v136
	v_add_f32_e32 v81, v81, v136
	v_cvt_pk_bf16_f32 v140, v78, v79
	v_cvt_pk_bf16_f32 v141, v80, v81
	s_nop 0
	v_mov_b32_dpp v142, v140 quad_perm:[1,0,3,2] row_mask:0xf bank_mask:0xf
	v_mov_b32_dpp v143, v141 quad_perm:[1,0,3,2] row_mask:0xf bank_mask:0xf
	v_perm_b32 v144, v142, v140, v139
	v_perm_b32 v145, v143, v141, v139
	s_nop 0
	v_mov_b32_dpp v146, v144 quad_perm:[2,3,0,1] row_mask:0xf bank_mask:0xf
	v_mov_b32_dpp v147, v145 quad_perm:[2,3,0,1] row_mask:0xf bank_mask:0xf
	v_cndmask_b32_e32 v148, v144, v147, vcc
	v_cndmask_b32_e32 v149, v146, v145, vcc
	global_store_dwordx2 v[130:131], v[148:149], off
	v_add_f32_e32 v14, v14, v137
	v_add_f32_e32 v15, v15, v137
	v_add_f32_e32 v16, v16, v137
	v_add_f32_e32 v17, v17, v137
	v_cvt_pk_bf16_f32 v140, v14, v15
	v_cvt_pk_bf16_f32 v141, v16, v17
	s_nop 0
	v_mov_b32_dpp v142, v140 quad_perm:[1,0,3,2] row_mask:0xf bank_mask:0xf
	v_mov_b32_dpp v143, v141 quad_perm:[1,0,3,2] row_mask:0xf bank_mask:0xf
	v_perm_b32 v144, v142, v140, v139
	v_perm_b32 v145, v143, v141, v139
	s_nop 0
	v_mov_b32_dpp v146, v144 quad_perm:[2,3,0,1] row_mask:0xf bank_mask:0xf
	v_mov_b32_dpp v147, v145 quad_perm:[2,3,0,1] row_mask:0xf bank_mask:0xf
	v_cndmask_b32_e32 v148, v144, v147, vcc
	v_cndmask_b32_e32 v149, v146, v145, vcc
	global_store_dwordx2 v[130:131], v[148:149], off offset:64
